# attention tile loop: K/V fragments prefetched 4-5 MFMAs ahead (on top of merged GEMM loops + early barrier invalidate)
# speedup vs baseline: 1.0121x; 1.0121x over previous
.LBB0_210:
	s_add_i32 s71, s64, 0x4000
	s_and_b32 s9, s71, 0x4000
	v_add_u32_e32 v179, s9, v177
	v_add_u32_e32 v197, v179, v176
	v_add_u32_e32 v202, v179, v175
	v_add_u32_e32 v203, v179, v173
	v_add_u32_e32 v204, v179, v171
	ds_read_b128 v[214:217], v197 offset:4096
	ds_read_b128 v[218:221], v202 offset:4096
	ds_read_b128 v[246:249], v203 offset:4096
	ds_read_b128 v[236:239], v204 offset:4096
	v_add_u32_e32 v205, s9, v174
	v_add_u32_e32 v206, v205, v176
	ds_read_b128 v[198:201], v206 offset:32768
	v_add_u32_e32 v207, v205, v175
	v_add_u32_e32 v208, v205, v173
	v_add_u32_e32 v205, v205, v171
	v_exp_f32_e32 v179, v80
	v_exp_f32_e32 v180, v81
	v_exp_f32_e32 v181, v82
	v_exp_f32_e32 v182, v83
	v_exp_f32_e32 v183, v84
	v_exp_f32_e32 v184, v85
	v_exp_f32_e32 v185, v86
	v_exp_f32_e32 v186, v87
	v_exp_f32_e32 v187, v88
	v_exp_f32_e32 v188, v89
	v_exp_f32_e32 v189, v90
	v_exp_f32_e32 v190, v91
	v_exp_f32_e32 v191, v92
	v_exp_f32_e32 v194, v93
	v_exp_f32_e32 v195, v94
	v_exp_f32_e32 v196, v95
	s_and_b32 s9, s64, 0x4000
	s_add_i32 s46, s9, 0
	v_add_u32_e32 v213, s46, v165
	s_andn2_b64 vcc, exec, s[0:1]
	s_waitcnt lgkmcnt(4)
	v_mfma_f32_32x32x16_bf16 v[80:95], v[214:217], v[112:115], v[64:79]
	ds_read_b128 v[214:217], v206 offset:36864
	v_exp_f32_e32 v209, v108
	s_waitcnt lgkmcnt(4)
	v_mfma_f32_32x32x16_bf16 v[80:95], v[218:221], v[116:119], v[80:95]
	ds_read_b128 v[218:221], v206 offset:40960
	v_exp_f32_e32 v210, v109
	s_waitcnt lgkmcnt(4)
	v_mfma_f32_32x32x16_bf16 v[80:95], v[246:249], v[120:123], v[80:95]
	ds_read_b128 v[246:249], v206 offset:45056
	v_exp_f32_e32 v206, v105
	s_waitcnt lgkmcnt(4)
	v_mfma_f32_32x32x16_bf16 v[80:95], v[236:239], v[124:127], v[80:95]
	ds_read_b128 v[236:239], v207 offset:32768
	v_exp_f32_e32 v211, v110
	s_waitcnt lgkmcnt(4)
	v_mfma_f32_32x32x16_bf16 v[48:63], v[198:201], v[148:151], v[48:63]
	ds_read_b128 v[198:201], v207 offset:36864
	v_exp_f32_e32 v212, v111
	s_waitcnt lgkmcnt(4)
	v_mfma_f32_32x32x16_bf16 v[32:47], v[214:217], v[148:151], v[32:47]
	ds_read_b128 v[214:217], v207 offset:40960
	s_waitcnt lgkmcnt(4)
	v_mfma_f32_32x32x16_bf16 v[16:31], v[218:221], v[148:151], v[16:31]
	ds_read_b128 v[218:221], v207 offset:45056
	v_exp_f32_e32 v207, v106
	s_waitcnt lgkmcnt(4)
	v_mfma_f32_32x32x16_bf16 v[0:15], v[246:249], v[148:151], v[0:15]
	ds_read_b128 v[246:249], v208 offset:32768
	s_waitcnt lgkmcnt(4)
	v_mfma_f32_32x32x16_bf16 v[48:63], v[236:239], v[144:147], v[48:63]
	ds_read_b128 v[236:239], v208 offset:36864
	s_waitcnt lgkmcnt(4)
	v_mfma_f32_32x32x16_bf16 v[32:47], v[198:201], v[144:147], v[32:47]
	ds_read_b128 v[198:201], v208 offset:40960
	s_waitcnt lgkmcnt(4)
	v_mfma_f32_32x32x16_bf16 v[16:31], v[214:217], v[144:147], v[16:31]
	ds_read_b128 v[214:217], v208 offset:45056
	v_exp_f32_e32 v208, v107
	s_waitcnt lgkmcnt(4)
	v_mfma_f32_32x32x16_bf16 v[0:15], v[218:221], v[144:147], v[0:15]
	ds_read_b128 v[218:221], v205 offset:32768
	s_waitcnt lgkmcnt(4)
	v_mfma_f32_32x32x16_bf16 v[48:63], v[246:249], v[140:143], v[48:63]
	ds_read_b128 v[246:249], v205 offset:36864
	s_waitcnt lgkmcnt(4)
	v_mfma_f32_32x32x16_bf16 v[32:47], v[236:239], v[140:143], v[32:47]
	ds_read_b128 v[236:239], v205 offset:40960
	s_waitcnt lgkmcnt(4)
	v_mfma_f32_32x32x16_bf16 v[16:31], v[198:201], v[140:143], v[16:31]
	ds_read_b128 v[148:151], v205 offset:45056
	v_exp_f32_e32 v205, v104
	v_exp_f32_e32 v198, v97
	v_exp_f32_e32 v199, v98
	s_waitcnt lgkmcnt(4)
	v_mfma_f32_32x32x16_bf16 v[0:15], v[214:217], v[140:143], v[0:15]
	ds_read_b128 v[214:217], v197
	v_exp_f32_e32 v197, v96
	v_exp_f32_e32 v200, v99
	v_exp_f32_e32 v201, v100
	s_waitcnt lgkmcnt(4)
	v_mfma_f32_32x32x16_bf16 v[48:63], v[218:221], v[136:139], v[48:63]
	ds_read_b128 v[218:221], v202
	v_exp_f32_e32 v202, v101
	s_waitcnt lgkmcnt(4)
	v_mfma_f32_32x32x16_bf16 v[32:47], v[246:249], v[136:139], v[32:47]
	ds_read_b128 v[246:249], v203
	v_exp_f32_e32 v203, v102
	s_waitcnt lgkmcnt(4)
	v_mfma_f32_32x32x16_bf16 v[16:31], v[236:239], v[136:139], v[16:31]
	ds_read_b128 v[236:239], v204
	v_exp_f32_e32 v204, v103
	s_waitcnt lgkmcnt(4)
	v_mfma_f32_32x32x16_bf16 v[0:15], v[148:151], v[136:139], v[0:15]
	v_cvt_pk_bf16_f32 v148, v197, v198
	v_cvt_pk_bf16_f32 v149, v199, v200
	v_cvt_pk_bf16_f32 v150, v201, v202
	v_cvt_pk_bf16_f32 v151, v203, v204
	v_cvt_pk_bf16_f32 v140, v179, v180
	v_cvt_pk_bf16_f32 v141, v181, v182
	v_cvt_pk_bf16_f32 v142, v183, v184
	s_waitcnt lgkmcnt(3)
	v_mfma_f32_32x32x16_bf16 v[96:111], v[214:217], v[112:115], v[64:79]
	v_add_u32_e32 v214, v213, v172
	v_cvt_pk_bf16_f32 v143, v185, v186
	v_cvt_pk_bf16_f32 v144, v205, v206
	v_cvt_pk_bf16_f32 v145, v207, v208
	v_cvt_pk_bf16_f32 v146, v209, v210
	v_cvt_pk_bf16_f32 v147, v211, v212
	v_cvt_pk_bf16_f32 v136, v187, v188
	s_waitcnt lgkmcnt(2)
	v_mfma_f32_32x32x16_bf16 v[96:111], v[218:221], v[116:119], v[96:111]
	v_cvt_pk_bf16_f32 v137, v189, v190
	v_cvt_pk_bf16_f32 v138, v191, v194
	v_cvt_pk_bf16_f32 v139, v195, v196
	s_waitcnt vmcnt(1)
	ds_write_b64 v214, v[152:153] offset:32768
	v_add_u32_e32 v152, v213, v169
	s_waitcnt vmcnt(0)
	ds_write_b64 v214, v[156:157] offset:40960
	ds_write2st64_b64 v152, v[154:155], v[158:159] offset0:64 offset1:80
	s_waitcnt lgkmcnt(4)
	v_mfma_f32_32x32x16_bf16 v[96:111], v[246:249], v[120:123], v[96:111]
	s_waitcnt lgkmcnt(3)
	v_mfma_f32_32x32x16_bf16 v[96:111], v[236:239], v[124:127], v[96:111]
	s_cbranch_vccnz .LBB0_212
	v_add_u32_e32 v152, s46, v170
	ds_write_b128 v152, v[128:131]
	ds_write_b128 v152, v[132:135] offset:8192
